# UP epilogue: additionally issue the first batch of conv-parameter loads before the two halo barriers
# speedup vs baseline: 1.0093x; 1.0048x over previous
; #define LAS __attribute__((address_space(3)))
; __device__ __forceinline__ void epi_upc(const EpiP& e, const f32x4 (&acc)[2][2][4][2], const pg8::Unit& u, int wr, int wc, int fr, int fq) {
;     ...
;   asm volatile("s_waitcnt lgkmcnt(0)" ::: "memory");
;   __builtin_amdgcn_s_barrier();
;   __builtin_amdgcn_s_barrier();
;   asm volatile("" ::: "memory");
;   const float* cw = e.f0; const float* cb = e.f1;
;   bf16_t* act = (bf16_t*)e.out;
; #pragma unroll
;   for (int n = 0; n < 2; ++n) {
;     const int ch = 128 * u.pn + lc0 + 4 * n;
;     const f32x4 wg0 = *(const f32x4*)(cw + ch), wg1 = *(const f32x4*)(cw + NUP + ch), wg2 = *(const f32x4*)(cw + 2 * NUP + ch), bg = *(const f32x4*)(cb + ch);
;     const f32x4 wv0 = *(const f32x4*)(cw + DFF + ch), wv1 = *(const f32x4*)(cw + NUP + DFF + ch), wv2 = *(const f32x4*)(cw + 2 * NUP + DFF + ch), bv = *(const f32x4*)(cb + DFF + ch);
; #pragma unroll
;     for (int ai = 0; ai < 2; ++ai)
; #pragma unroll
;       for (int m = 0; m < 4; ++m) {
;         const int g = ai * 8 + wr * 4 + m, gp = g > 0 ? g - 1 : 0;
;         const f32x4 xg = acc[ai][0][m][n], xv = acc[ai][1][m][n];
;         float y[4];
;         if (m > 0) {
;           const f32x4 pg = acc[ai][0][m - 1][n], pv = acc[ai][1][m - 1][n];
; #pragma unroll
;           for (int k = 0; k < 4; ++k) {
;             const float g1 = dpp_prev1(pg[k], xg[k]), g2 = dpp_prev2(pg[k], xg[k]), v1 = dpp_prev1(pv[k], xv[k]), v2 = dpp_prev2(pv[k], xv[k]);
;             const float cg = bg[k] + wg0[k] * g2 + wg1[k] * g1 + wg2[k] * xg[k];
;             const float cv = bv[k] + wv0[k] * v2 + wv1[k] * v1 + wv2[k] * xv[k];
;             y[k] = silu_mul(cg, cv);
;           }
;         } else {
;           const LAS unsigned char* hp = ex + (gp * 2 * 256 + lc0 + 4 * n) * 2;
;           const u32x2 hg14 = *(const LAS u32x2*)hp, hg15 = *(const LAS u32x2*)(hp + 512), hv14 = *(const LAS u32x2*)(hp + 256), hv15 = *(const LAS u32x2*)(hp + 512 + 256);
;           const float h14g[4] = {bf_lo(hg14.x), bf_hi(hg14.x), bf_lo(hg14.y), bf_hi(hg14.y)}, h15g[4] = {bf_lo(hg15.x), bf_hi(hg15.x), bf_lo(hg15.y), bf_hi(hg15.y)};
;           const float h14v[4] = {bf_lo(hv14.x), bf_hi(hv14.x), bf_lo(hv14.y), bf_hi(hv14.y)}, h15v[4] = {bf_lo(hv15.x), bf_hi(hv15.x), bf_lo(hv15.y), bf_hi(hv15.y)};
; #pragma unroll
;           for (int k = 0; k < 4; ++k) {
.LBB0_1289:
	s_or_b64 exec, exec, s[58:59]
	v_or_b32_e32 v176, s0, v214
	v_ashrrev_i32_e32 v177, 31, v176
	v_lshlrev_b64 v[134:135], 2, v[176:177]
	v_lshl_add_u64 v[178:179], s[16:17], 0, v[134:135]
	v_lshl_add_u64 v[122:123], s[20:21], 0, v[134:135]
	global_load_dwordx4 v[138:141], v[178:179], off
	v_lshl_add_u64 v[124:125], s[22:23], 0, v[134:135]
	global_load_dwordx4 v[142:145], v[122:123], off
	global_load_dwordx4 v[146:149], v[124:125], off
	v_lshl_add_u64 v[180:181], s[18:19], 0, v[134:135]
	v_lshl_add_u64 v[122:123], s[24:25], 0, v[134:135]
	v_lshl_add_u64 v[126:127], s[30:31], 0, v[134:135]
	v_lshl_add_u64 v[130:131], s[26:27], 0, v[134:135]
	v_lshl_add_u64 v[134:135], s[28:29], 0, v[134:135]
	global_load_dwordx4 v[150:153], v[180:181], off
	v_mov_b32_dpp v238, v158 row_shr:1 row_mask:0xf bank_mask:0xf bound_ctrl:1
	global_load_dwordx4 v[122:125], v[122:123], off
	v_mov_b32_dpp v239, v158 row_shr:2 row_mask:0xf bank_mask:0xf bound_ctrl:1
	global_load_dwordx4 v[126:129], v[126:127], off
	v_mov_b32_dpp v241, v154 row_shr:1 row_mask:0xf bank_mask:0xf bound_ctrl:1
	global_load_dwordx4 v[130:133], v[130:131], off
	v_mov_b32_dpp v240, v154 row_shr:2 row_mask:0xf bank_mask:0xf bound_ctrl:1
	global_load_dwordx4 v[134:137], v[134:135], off
	v_mov_b32_dpp v235, v159 row_shr:1 row_mask:0xf bank_mask:0xf bound_ctrl:1
	v_mov_b32_dpp v232, v159 row_shr:2 row_mask:0xf bank_mask:0xf bound_ctrl:1
	v_mov_b32_dpp v237, v155 row_shr:1 row_mask:0xf bank_mask:0xf bound_ctrl:1
	v_mov_b32_dpp v236, v155 row_shr:2 row_mask:0xf bank_mask:0xf bound_ctrl:1
	v_mov_b32_dpp v229, v160 row_shr:1 row_mask:0xf bank_mask:0xf bound_ctrl:1
	v_mov_b32_dpp v227, v160 row_shr:2 row_mask:0xf bank_mask:0xf bound_ctrl:1
	v_mov_b32_dpp v234, v156 row_shr:1 row_mask:0xf bank_mask:0xf bound_ctrl:1
	v_mov_b32_dpp v233, v156 row_shr:2 row_mask:0xf bank_mask:0xf bound_ctrl:1
	v_mov_b32_dpp v228, v161 row_shr:1 row_mask:0xf bank_mask:0xf bound_ctrl:1
	v_mov_b32_dpp v226, v161 row_shr:2 row_mask:0xf bank_mask:0xf bound_ctrl:1
	v_mov_b32_dpp v231, v157 row_shr:1 row_mask:0xf bank_mask:0xf bound_ctrl:1
	v_mov_b32_dpp v230, v157 row_shr:2 row_mask:0xf bank_mask:0xf bound_ctrl:1
	v_lshl_add_u64 v[182:183], v[176:177], 1, s[12:13]
	s_waitcnt lgkmcnt(0)
	s_barrier
	s_barrier
	s_waitcnt vmcnt(0)
	v_mov_b32_e32 v204, v138
	v_mov_b32_e32 v208, v142
	v_mov_b32_e32 v210, v146
	v_mov_b32_e32 v197, v139
	v_mov_b32_e32 v201, v143
	v_mov_b32_e32 v203, v147
	v_mov_b32_e32 v187, v140
	v_mov_b32_e32 v193, v144
	v_mov_b32_e32 v206, v150
	v_mov_b32_e32 v199, v151
	v_mov_b32_e32 v205, v122
	v_mov_b32_e32 v196, v123
	v_mov_b32_e32 v207, v126
	v_mov_b32_e32 v198, v127
	v_mov_b32_e32 v209, v130
	v_mov_b32_e32 v200, v131
	v_mov_b32_e32 v211, v134
	v_mov_b32_e32 v202, v135
	v_mov_b32_e32 v186, v124
	v_mov_b32_e32 v190, v128
	v_mov_b32_e32 v191, v152
	v_mov_b32_e32 v192, v132
	v_mov_b32_e32 v194, v136
	v_mov_b32_e32 v195, v148
	v_mov_b32_e32 v184, v149
	v_mov_b32_e32 v185, v137
	v_mov_b32_e32 v188, v145
	v_mov_b32_e32 v189, v133
	s_and_saveexec_b64 s[58:59], s[38:39]
	s_xor_b64 s[58:59], exec, s[58:59]
	s_cbranch_execz .LBB0_1291
; #define LAS __attribute__((address_space(3)))
; __device__ __forceinline__ float bf_lo(unsigned u) { return __uint_as_float(u << 16); }
; __device__ __forceinline__ float bf_hi(unsigned u) { return __uint_as_float(u & 0xffff0000u); }
; __device__ __forceinline__ float dpp_shr1(float x) { return __int_as_float(__builtin_amdgcn_update_dpp(0, __float_as_int(x), 0x111, 0xF, 0xF, true)); }
; __device__ __forceinline__ float dpp_shr2(float x) { return __int_as_float(__builtin_amdgcn_update_dpp(0, __float_as_int(x), 0x112, 0xF, 0xF, true)); }
; __device__ __forceinline__ float silu_mul(float g, float v) { return g * frcp(1.0f + fexp2(-g * LOG2E)) * v; }
; __device__ __forceinline__ void epi_upc(const EpiP& e, const f32x4 (&acc)[2][2][4][2], const pg8::Unit& u, int wr, int wc, int fr, int fq) {
;     ...
;           const LAS unsigned char* hp = ex + (gp * 2 * 256 + lc0 + 4 * n) * 2;
;           const u32x2 hg14 = *(const LAS u32x2*)hp, hg15 = *(const LAS u32x2*)(hp + 512), hv14 = *(const LAS u32x2*)(hp + 256), hv15 = *(const LAS u32x2*)(hp + 512 + 256);
;           const float h14g[4] = {bf_lo(hg14.x), bf_hi(hg14.x), bf_lo(hg14.y), bf_hi(hg14.y)}, h15g[4] = {bf_lo(hg15.x), bf_hi(hg15.x), bf_lo(hg15.y), bf_hi(hg15.y)};
;           const float h14v[4] = {bf_lo(hv14.x), bf_hi(hv14.x), bf_lo(hv14.y), bf_hi(hv14.y)}, h15v[4] = {bf_lo(hv15.x), bf_hi(hv15.x), bf_lo(hv15.y), bf_hi(hv15.y)};
; #pragma unroll
;           for (int k = 0; k < 4; ++k) {
;             float g1 = dpp_shr1(xg[k]), g2 = dpp_shr2(xg[k]), v1 = dpp_shr1(xv[k]), v2 = dpp_shr2(xv[k]);
;             if (fr == 0) { g1 = h15g[k]; g2 = h14g[k]; v1 = h15v[k]; v2 = h14v[k]; }
;             if (fr == 1) { g2 = h15g[k]; v2 = h15v[k]; }
;             const float cg = bg[k] + wg0[k] * g2 + wg1[k] * g1 + wg2[k] * xg[k];
;             const float cv = bv[k] + wv0[k] * v2 + wv1[k] * v1 + wv2[k] * xv[k];
;             y[k] = silu_mul(cg, cv);
;           }
;         }
;         const int row = u.pm * 256 + ai * 128 + wr * 64 + m * 16 + fr;
;         if (!(g == 0 && fr < 2)) { u32x2 w; w.x = pk2(y[0], y[1]); w.y = pk2(y[2], y[3]); *(u32x2*)(act + (size_t)row * DFF + ch) = w; }
	v_add_u32_e32 v177, s35, v215
	v_mov_b64_e32 v[218:219], v[244:245]
	ds_read2_b64 v[242:245], v177 offset1:32
	ds_read2_b64 v[220:223], v177 offset0:64 offset1:96
	s_lshl_b32 s0, s56, 8
	s_waitcnt lgkmcnt(0)
	v_and_b32_e32 v177, 0xffff0000, v242
	v_and_b32_e32 v248, 0xffff0000, v244
	v_lshlrev_b32_e32 v188, 16, v220
	v_lshlrev_b32_e32 v244, 16, v244
	v_lshlrev_b32_e32 v242, 16, v242
	v_lshlrev_b32_e32 v189, 16, v222
	v_cndmask_b32_e64 v184, v238, v188, s[4:5]
	v_cndmask_b32_e64 v238, v239, v242, s[4:5]
	v_cndmask_b32_e64 v239, v240, v244, s[4:5]
	v_cndmask_b32_e64 v185, v241, v189, s[4:5]
	v_cndmask_b32_e64 v189, v239, v189, s[6:7]
	v_cndmask_b32_e64 v188, v238, v188, s[6:7]
	v_pk_fma_f32 v[188:189], v[204:205], v[188:189], v[206:207]
	v_and_b32_e32 v220, 0xffff0000, v220
	v_pk_fma_f32 v[184:185], v[208:209], v[184:185], v[188:189]
	v_mov_b32_e32 v188, v158
	v_mov_b32_e32 v189, v154
	v_pk_fma_f32 v[184:185], v[188:189], v[210:211], v[184:185]
	v_and_b32_e32 v222, 0xffff0000, v222
	v_mul_f32_e32 v188, 0xbfb8aa3b, v184
	v_exp_f32_e32 v188, v188
	v_cndmask_b32_e64 v189, v235, v220, s[4:5]
	v_cndmask_b32_e64 v235, v236, v248, s[4:5]
	v_cndmask_b32_e64 v177, v232, v177, s[4:5]
	v_add_f32_e32 v188, 1.0, v188
	v_lshlrev_b32_e32 v239, 16, v221
	v_and_b32_e32 v240, 0xffff0000, v221
	v_rcp_f32_e32 v241, v188
	v_cndmask_b32_e64 v221, v177, v220, s[6:7]
	v_cndmask_b32_e64 v220, v235, v222, s[6:7]
	v_cndmask_b32_e64 v188, v237, v222, s[4:5]
	v_pk_fma_f32 v[220:221], v[196:197], v[220:221], v[198:199]
	v_lshlrev_b32_e32 v249, 16, v243
	v_lshlrev_b32_e32 v252, 16, v245
	v_pk_fma_f32 v[188:189], v[200:201], v[188:189], v[220:221]
	v_mov_b32_e32 v220, v155
	v_mov_b32_e32 v221, v159
	v_lshlrev_b32_e32 v238, 16, v223
	v_pk_fma_f32 v[188:189], v[220:221], v[202:203], v[188:189]
	v_cndmask_b32_e64 v220, v233, v252, s[4:5]
	v_cndmask_b32_e64 v221, v227, v249, s[4:5]
	v_mul_f32_e32 v184, v184, v241
	v_cndmask_b32_e64 v221, v221, v239, s[6:7]
	v_cndmask_b32_e64 v220, v220, v238, s[6:7]
	v_mul_f32_e32 v236, v185, v184
	v_cndmask_b32_e64 v185, v229, v239, s[4:5]
	v_cndmask_b32_e64 v184, v234, v238, s[4:5]
	v_pk_fma_f32 v[220:221], v[186:187], v[220:221], v[190:191]
	v_and_b32_e32 v243, 0xffff0000, v243
	v_pk_fma_f32 v[184:185], v[192:193], v[184:185], v[220:221]
	v_mov_b32_e32 v220, v156
	v_mov_b32_e32 v221, v160
	v_pk_fma_f32 v[184:185], v[220:221], v[194:195], v[184:185]
	v_and_b32_e32 v245, 0xffff0000, v245
	v_mul_f32_e32 v177, 0xbfb8aa3b, v189
	v_and_b32_e32 v232, 0xffff0000, v223
	v_mul_f32_e32 v220, 0xbfb8aa3b, v185
	v_exp_f32_e32 v177, v177
	v_exp_f32_e32 v237, v220
	v_cndmask_b32_e64 v220, v231, v232, s[4:5]
	v_cndmask_b32_e64 v230, v230, v245, s[4:5]
	v_cndmask_b32_e64 v231, v226, v243, s[4:5]
	v_cndmask_b32_e64 v231, v231, v240, s[6:7]
	v_cndmask_b32_e64 v230, v230, v232, s[6:7]
	v_mov_b32_e32 v232, v125
	v_mov_b32_e32 v233, v141
	v_mov_b32_e32 v234, v129
	v_mov_b32_e32 v235, v153
	v_cndmask_b32_e64 v221, v228, v240, s[4:5]
	v_mov_b32_e32 v228, v133
	v_mov_b32_e32 v229, v145
	v_pk_fma_f32 v[230:231], v[232:233], v[230:231], v[234:235]
	v_mov_b32_e32 v222, v157
	v_mov_b32_e32 v223, v161
	v_mov_b32_e32 v226, v137
	v_mov_b32_e32 v227, v149
	v_pk_fma_f32 v[220:221], v[228:229], v[220:221], v[230:231]
	v_add_f32_e32 v177, 1.0, v177
	v_pk_fma_f32 v[220:221], v[222:223], v[226:227], v[220:221]
	v_rcp_f32_e32 v177, v177
	v_mul_f32_e32 v222, 0xbfb8aa3b, v221
	v_exp_f32_e32 v222, v222
	v_mov_b64_e32 v[244:245], v[218:219]
	v_mul_f32_e32 v177, v189, v177
	v_add_f32_e32 v189, 1.0, v237
	v_rcp_f32_e32 v189, v189
	v_add_f32_e32 v222, 1.0, v222
	v_rcp_f32_e32 v222, v222
	v_mul_f32_e32 v177, v188, v177
	v_mul_f32_e32 v185, v185, v189
	v_mul_f32_e32 v185, v184, v185
	v_mul_f32_e32 v184, v221, v222
	v_mul_f32_e32 v188, v220, v184
	v_add_u32_e32 v189, s0, v212
	v_cvt_pk_bf16_f32 v184, v236, v177
	v_cvt_pk_bf16_f32 v185, v185, v188
	v_mad_i64_i32 v[188:189], s[60:61], v189, s74, v[182:183]
	global_store_dwordx2 v[188:189], v[184:185], off
	v_mov_b32_e32 v184, v149
	v_mov_b32_e32 v185, v137
	v_mov_b32_e32 v188, v145
	v_mov_b32_e32 v189, v133

; __device__ __forceinline__ void epi_upc(const EpiP& e, const f32x4 (&acc)[2][2][4][2], const pg8::Unit& u, int wr, int wc, int fr, int fq) {
;     ...
;     const f32x4 wg0 = *(const f32x4*)(cw + ch), wg1 = *(const f32x4*)(cw + NUP + ch), wg2 = *(const f32x4*)(cw + 2 * NUP + ch), bg = *(const f32x4*)(cb + ch);
;     const f32x4 wv0 = *(const f32x4*)(cw + DFF + ch), wv1 = *(const f32x4*)(cw + NUP + DFF + ch), wv2 = *(const f32x4*)(cw + 2 * NUP + DFF + ch), bv = *(const f32x4*)(cb + DFF + ch);
; #pragma unroll
;     for (int ai = 0; ai < 2; ++ai)
; #pragma unroll
;       for (int m = 0; m < 4; ++m) {
;         const int g = ai * 8 + wr * 4 + m, gp = g > 0 ? g - 1 : 0;
;         const f32x4 xg = acc[ai][0][m][n], xv = acc[ai][1][m][n];
;         float y[4];
;         if (m > 0) {
;           const f32x4 pg = acc[ai][0][m - 1][n], pv = acc[ai][1][m - 1][n];
; #pragma unroll
;           for (int k = 0; k < 4; ++k) {
;             const float g1 = dpp_prev1(pg[k], xg[k]), g2 = dpp_prev2(pg[k], xg[k]), v1 = dpp_prev1(pv[k], xv[k]), v2 = dpp_prev2(pv[k], xv[k]);
;             const float cg = bg[k] + wg0[k] * g2 + wg1[k] * g1 + wg2[k] * xg[k];
;             const float cv = bv[k] + wv0[k] * v2 + wv1[k] * v1 + wv2[k] * xv[k];
;             y[k] = silu_mul(cg, cv);
;           }
;         } else {
;           const LAS unsigned char* hp = ex + (gp * 2 * 256 + lc0 + 4 * n) * 2;
;           const u32x2 hg14 = *(const LAS u32x2*)hp, hg15 = *(const LAS u32x2*)(hp + 512), hv14 = *(const LAS u32x2*)(hp + 256), hv15 = *(const LAS u32x2*)(hp + 512 + 256);
;           const float h14g[4] = {bf_lo(hg14.x), bf_hi(hg14.x), bf_lo(hg14.y), bf_hi(hg14.y)}, h15g[4] = {bf_lo(hg15.x), bf_hi(hg15.x), bf_lo(hg15.y), bf_hi(hg15.y)};
;           const float h14v[4] = {bf_lo(hv14.x), bf_hi(hv14.x), bf_lo(hv14.y), bf_hi(hv14.y)}, h15v[4] = {bf_lo(hv15.x), bf_hi(hv15.x), bf_lo(hv15.y), bf_hi(hv15.y)};
; #pragma unroll
;           for (int k = 0; k < 4; ++k) {
;             float g1 = dpp_shr1(xg[k]), g2 = dpp_shr2(xg[k]), v1 = dpp_shr1(xv[k]), v2 = dpp_shr2(xv[k]);
;             if (fr == 0) { g1 = h15g[k]; g2 = h14g[k]; v1 = h15v[k]; v2 = h14v[k]; }
;             if (fr == 1) { g2 = h15g[k]; v2 = h15v[k]; }
;             const float cg = bg[k] + wg0[k] * g2 + wg1[k] * g1 + wg2[k] * xg[k];
;             const float cv = bv[k] + wv0[k] * v2 + wv1[k] * v1 + wv2[k] * xv[k];
.LBB0_1295:
	s_or_b64 exec, exec, s[56:57]
	v_lshlrev_b32_e32 v206, 2, v176
	v_mov_b32_e32 v207, 0
	global_load_dwordx4 v[104:107], v[178:179], off offset:16
	v_lshl_add_u64 v[208:209], s[20:21], 0, v[206:207]
	global_load_dwordx4 v[108:111], v[208:209], off offset:16
	v_lshl_add_u64 v[208:209], s[22:23], 0, v[206:207]
	global_load_dwordx4 v[112:115], v[208:209], off offset:16
	global_load_dwordx4 v[116:119], v[180:181], off offset:16
	v_lshl_add_u64 v[208:209], s[24:25], 0, v[206:207]
	global_load_dwordx4 v[190:193], v[208:209], off offset:16
	v_lshl_add_u64 v[208:209], s[30:31], 0, v[206:207]
	global_load_dwordx4 v[194:197], v[208:209], off offset:16
	v_lshl_add_u64 v[208:209], s[26:27], 0, v[206:207]
	global_load_dwordx4 v[198:201], v[208:209], off offset:16
	v_lshl_add_u64 v[208:209], s[28:29], 0, v[206:207]
	global_load_dwordx4 v[202:205], v[208:209], off offset:16
	v_mov_b32_e32 v100, v97
	v_mov_b32_e32 v101, v97
	v_mov_b32_e32 v98, v97
	v_mov_b32_dpp v100, v92 row_ror:2 row_mask:0xf bank_mask:0xf
	v_mov_b32_e32 v99, v97
	v_mov_b32_dpp v101, v93 row_ror:2 row_mask:0xf bank_mask:0xf
	v_mov_b32_dpp v98, v92 row_ror:1 row_mask:0xf bank_mask:0xf
	v_mov_b32_dpp v100, v84 row_shr:2 row_mask:0xf bank_mask:0xf
	v_mov_b32_e32 v92, v97
	v_mov_b32_e32 v102, v97
	v_mov_b32_dpp v99, v93 row_ror:1 row_mask:0xf bank_mask:0xf
	v_mov_b32_dpp v101, v85 row_shr:2 row_mask:0xf bank_mask:0xf
	v_mov_b32_e32 v93, v97
	v_mov_b32_e32 v103, v97
	v_mov_b32_dpp v98, v84 row_shr:1 row_mask:0xf bank_mask:0xf
	v_mov_b32_dpp v92, v88 row_ror:1 row_mask:0xf bank_mask:0xf
	v_mov_b32_dpp v102, v88 row_ror:2 row_mask:0xf bank_mask:0xf
	v_mov_b32_dpp v99, v85 row_shr:1 row_mask:0xf bank_mask:0xf
	v_mov_b32_dpp v93, v89 row_ror:1 row_mask:0xf bank_mask:0xf
	v_mov_b32_dpp v103, v89 row_ror:2 row_mask:0xf bank_mask:0xf
	v_pk_fma_f32 v[88:89], v[138:139], v[100:101], v[150:151]
	v_mov_b32_dpp v102, v80 row_shr:2 row_mask:0xf bank_mask:0xf
	v_pk_fma_f32 v[88:89], v[142:143], v[98:99], v[88:89]
	v_mov_b32_dpp v103, v81 row_shr:2 row_mask:0xf bank_mask:0xf
	v_pk_fma_f32 v[88:89], v[84:85], v[146:147], v[88:89]
	v_mov_b32_dpp v92, v80 row_shr:1 row_mask:0xf bank_mask:0xf
	v_mul_f32_e32 v98, 0xbfb8aa3b, v88
	v_mul_f32_e32 v99, 0xbfb8aa3b, v89
	v_exp_f32_e32 v98, v98
	v_exp_f32_e32 v99, v99
	v_mov_b32_dpp v93, v81 row_shr:1 row_mask:0xf bank_mask:0xf
	v_pk_fma_f32 v[100:101], v[122:123], v[102:103], v[126:127]
	v_add_f32_e32 v98, 1.0, v98
	v_add_f32_e32 v99, 1.0, v99
	v_rcp_f32_e32 v98, v98
	v_rcp_f32_e32 v99, v99
	v_pk_fma_f32 v[92:93], v[130:131], v[92:93], v[100:101]
	v_mov_b32_e32 v100, v97
	v_pk_fma_f32 v[92:93], v[80:81], v[134:135], v[92:93]
	v_pk_mul_f32 v[88:89], v[88:89], v[98:99]
	v_mov_b32_e32 v98, v97
	v_mov_b32_e32 v99, v97
	v_pk_mul_f32 v[88:89], v[92:93], v[88:89]
	v_mov_b32_e32 v92, v97
	v_mov_b32_dpp v98, v94 row_ror:2 row_mask:0xf bank_mask:0xf
	v_mov_b32_e32 v93, v97
	v_mov_b32_dpp v99, v95 row_ror:2 row_mask:0xf bank_mask:0xf
	v_mov_b32_dpp v92, v94 row_ror:1 row_mask:0xf bank_mask:0xf
	v_mov_b32_dpp v98, v86 row_shr:2 row_mask:0xf bank_mask:0xf
	v_mov_b32_e32 v94, v97
	v_mov_b32_dpp v93, v95 row_ror:1 row_mask:0xf bank_mask:0xf
	v_mov_b32_dpp v99, v87 row_shr:2 row_mask:0xf bank_mask:0xf
	v_mov_b32_e32 v95, v97
	v_mov_b32_e32 v101, v97
	v_mov_b32_dpp v92, v86 row_shr:1 row_mask:0xf bank_mask:0xf
	v_mov_b32_dpp v94, v90 row_ror:1 row_mask:0xf bank_mask:0xf
	v_mov_b32_dpp v100, v90 row_ror:2 row_mask:0xf bank_mask:0xf
	v_mov_b32_dpp v93, v87 row_shr:1 row_mask:0xf bank_mask:0xf
	v_mov_b32_dpp v95, v91 row_ror:1 row_mask:0xf bank_mask:0xf
	v_mov_b32_dpp v101, v91 row_ror:2 row_mask:0xf bank_mask:0xf
	v_pk_fma_f32 v[90:91], v[140:141], v[98:99], v[152:153]
	v_mov_b32_e32 v145, v188
	v_pk_fma_f32 v[90:91], v[144:145], v[92:93], v[90:91]
	v_mov_b32_e32 v149, v184
	v_pk_fma_f32 v[90:91], v[86:87], v[148:149], v[90:91]
	v_mov_b32_dpp v100, v82 row_shr:2 row_mask:0xf bank_mask:0xf
	v_mul_f32_e32 v92, 0xbfb8aa3b, v90
	v_mul_f32_e32 v93, 0xbfb8aa3b, v91
	v_exp_f32_e32 v92, v92
	v_exp_f32_e32 v93, v93
	v_mov_b32_dpp v101, v83 row_shr:2 row_mask:0xf bank_mask:0xf
	v_mov_b32_dpp v94, v82 row_shr:1 row_mask:0xf bank_mask:0xf
	v_add_f32_e32 v92, 1.0, v92
	v_add_f32_e32 v93, 1.0, v93
	v_rcp_f32_e32 v92, v92
	v_rcp_f32_e32 v93, v93
	v_mov_b32_dpp v95, v83 row_shr:1 row_mask:0xf bank_mask:0xf
	v_pk_fma_f32 v[98:99], v[124:125], v[100:101], v[128:129]
	v_cvt_pk_bf16_f32 v88, v88, v89
	v_pk_fma_f32 v[94:95], v[132:133], v[94:95], v[98:99]
	v_pk_mul_f32 v[90:91], v[90:91], v[92:93]
	v_pk_fma_f32 v[94:95], v[82:83], v[136:137], v[94:95]
	v_add_u32_e32 v92, 0x90, v212
	v_pk_mul_f32 v[90:91], v[94:95], v[90:91]
	v_add_u32_e32 v155, v92, v177
	v_cvt_pk_bf16_f32 v89, v90, v91
	v_mad_i64_i32 v[90:91], s[0:1], v155, s74, v[182:183]
	global_store_dwordx2 v[90:91], v[88:89], off
	v_mov_b32_e32 v90, v97
	v_mov_b32_e32 v91, v97
	v_mov_b32_e32 v88, v97
	v_mov_b32_dpp v90, v84 row_ror:2 row_mask:0xf bank_mask:0xf
	v_mov_b32_e32 v89, v97
	v_mov_b32_dpp v91, v85 row_ror:2 row_mask:0xf bank_mask:0xf
	v_mov_b32_dpp v88, v84 row_ror:1 row_mask:0xf bank_mask:0xf
	v_mov_b32_dpp v90, v76 row_shr:2 row_mask:0xf bank_mask:0xf
	v_mov_b32_e32 v84, v97
	v_mov_b32_e32 v92, v97
	v_mov_b32_dpp v89, v85 row_ror:1 row_mask:0xf bank_mask:0xf
	v_mov_b32_dpp v91, v77 row_shr:2 row_mask:0xf bank_mask:0xf
	v_mov_b32_e32 v85, v97
	v_mov_b32_e32 v93, v97
	v_mov_b32_dpp v88, v76 row_shr:1 row_mask:0xf bank_mask:0xf
	v_mov_b32_dpp v84, v80 row_ror:1 row_mask:0xf bank_mask:0xf
	v_mov_b32_dpp v92, v80 row_ror:2 row_mask:0xf bank_mask:0xf
	v_mov_b32_dpp v89, v77 row_shr:1 row_mask:0xf bank_mask:0xf
; #define LAS __attribute__((address_space(3)))
; __device__ __forceinline__ float bf_lo(unsigned u) { return __uint_as_float(u << 16); }
; __device__ __forceinline__ float bf_hi(unsigned u) { return __uint_as_float(u & 0xffff0000u); }
; __device__ __forceinline__ float silu_mul(float g, float v) { return g * frcp(1.0f + fexp2(-g * LOG2E)) * v; }
; __device__ __forceinline__ void epi_upc(const EpiP& e, const f32x4 (&acc)[2][2][4][2], const pg8::Unit& u, int wr, int wc, int fr, int fq) {
;     ...
;         if (m > 0) {
;           const f32x4 pg = acc[ai][0][m - 1][n], pv = acc[ai][1][m - 1][n];
; #pragma unroll
;           for (int k = 0; k < 4; ++k) {
;             const float g1 = dpp_prev1(pg[k], xg[k]), g2 = dpp_prev2(pg[k], xg[k]), v1 = dpp_prev1(pv[k], xv[k]), v2 = dpp_prev2(pv[k], xv[k]);
;             const float cg = bg[k] + wg0[k] * g2 + wg1[k] * g1 + wg2[k] * xg[k];
;             const float cv = bv[k] + wv0[k] * v2 + wv1[k] * v1 + wv2[k] * xv[k];
;             y[k] = silu_mul(cg, cv);
;           }
;         } else {
;           const LAS unsigned char* hp = ex + (gp * 2 * 256 + lc0 + 4 * n) * 2;
;           const u32x2 hg14 = *(const LAS u32x2*)hp, hg15 = *(const LAS u32x2*)(hp + 512), hv14 = *(const LAS u32x2*)(hp + 256), hv15 = *(const LAS u32x2*)(hp + 512 + 256);
;           const float h14g[4] = {bf_lo(hg14.x), bf_hi(hg14.x), bf_lo(hg14.y), bf_hi(hg14.y)}, h15g[4] = {bf_lo(hg15.x), bf_hi(hg15.x), bf_lo(hg15.y), bf_hi(hg15.y)};
;           const float h14v[4] = {bf_lo(hv14.x), bf_hi(hv14.x), bf_lo(hv14.y), bf_hi(hv14.y)}, h15v[4] = {bf_lo(hv15.x), bf_hi(hv15.x), bf_lo(hv15.y), bf_hi(hv15.y)};
; #pragma unroll
;           for (int k = 0; k < 4; ++k) {
;             float g1 = dpp_shr1(xg[k]), g2 = dpp_shr2(xg[k]), v1 = dpp_shr1(xv[k]), v2 = dpp_shr2(xv[k]);
;             if (fr == 0) { g1 = h15g[k]; g2 = h14g[k]; v1 = h15v[k]; v2 = h14v[k]; }
;             if (fr == 1) { g2 = h15g[k]; v2 = h15v[k]; }
;             const float cg = bg[k] + wg0[k] * g2 + wg1[k] * g1 + wg2[k] * xg[k];
;             const float cv = bv[k] + wv0[k] * v2 + wv1[k] * v1 + wv2[k] * xv[k];
;             y[k] = silu_mul(cg, cv);
;           }
;         }
;         const int row = u.pm * 256 + ai * 128 + wr * 64 + m * 16 + fr;
;         if (!(g == 0 && fr < 2)) { u32x2 w; w.x = pk2(y[0], y[1]); w.y = pk2(y[2], y[3]); *(u32x2*)(act + (size_t)row * DFF + ch) = w; }
	v_mov_b32_dpp v85, v81 row_ror:1 row_mask:0xf bank_mask:0xf
	v_mov_b32_dpp v93, v81 row_ror:2 row_mask:0xf bank_mask:0xf
	v_pk_fma_f32 v[80:81], v[138:139], v[90:91], v[150:151]
	v_mov_b32_dpp v92, v68 row_shr:2 row_mask:0xf bank_mask:0xf
	v_pk_fma_f32 v[80:81], v[142:143], v[88:89], v[80:81]
	v_mov_b32_dpp v93, v69 row_shr:2 row_mask:0xf bank_mask:0xf
	v_pk_fma_f32 v[80:81], v[76:77], v[146:147], v[80:81]
	v_mov_b32_dpp v84, v68 row_shr:1 row_mask:0xf bank_mask:0xf
	v_mul_f32_e32 v88, 0xbfb8aa3b, v80
	v_mul_f32_e32 v89, 0xbfb8aa3b, v81
	v_exp_f32_e32 v88, v88
	v_exp_f32_e32 v89, v89
	v_mov_b32_dpp v85, v69 row_shr:1 row_mask:0xf bank_mask:0xf
	v_pk_fma_f32 v[90:91], v[122:123], v[92:93], v[126:127]
	v_add_f32_e32 v88, 1.0, v88
	v_add_f32_e32 v89, 1.0, v89
	v_rcp_f32_e32 v88, v88
	v_rcp_f32_e32 v89, v89
	v_pk_fma_f32 v[84:85], v[130:131], v[84:85], v[90:91]
	v_mov_b32_e32 v90, v97
	v_pk_fma_f32 v[84:85], v[68:69], v[134:135], v[84:85]
	v_pk_mul_f32 v[80:81], v[80:81], v[88:89]
	v_mov_b32_e32 v88, v97
	v_mov_b32_e32 v89, v97
	v_pk_mul_f32 v[80:81], v[84:85], v[80:81]
	v_mov_b32_e32 v84, v97
	v_mov_b32_dpp v88, v86 row_ror:2 row_mask:0xf bank_mask:0xf
	v_mov_b32_e32 v85, v97
	v_mov_b32_dpp v89, v87 row_ror:2 row_mask:0xf bank_mask:0xf
	v_mov_b32_dpp v84, v86 row_ror:1 row_mask:0xf bank_mask:0xf
	v_mov_b32_dpp v88, v78 row_shr:2 row_mask:0xf bank_mask:0xf
	v_mov_b32_e32 v86, v97
	v_mov_b32_dpp v85, v87 row_ror:1 row_mask:0xf bank_mask:0xf
	v_mov_b32_dpp v89, v79 row_shr:2 row_mask:0xf bank_mask:0xf
	v_mov_b32_e32 v87, v97
	v_mov_b32_e32 v91, v97
	v_mov_b32_dpp v84, v78 row_shr:1 row_mask:0xf bank_mask:0xf
	v_mov_b32_dpp v86, v82 row_ror:1 row_mask:0xf bank_mask:0xf
	v_mov_b32_dpp v90, v82 row_ror:2 row_mask:0xf bank_mask:0xf
	v_mov_b32_dpp v85, v79 row_shr:1 row_mask:0xf bank_mask:0xf
	v_mov_b32_dpp v87, v83 row_ror:1 row_mask:0xf bank_mask:0xf
	v_mov_b32_dpp v91, v83 row_ror:2 row_mask:0xf bank_mask:0xf
	v_pk_fma_f32 v[82:83], v[140:141], v[88:89], v[152:153]
	v_mov_b32_dpp v90, v70 row_shr:2 row_mask:0xf bank_mask:0xf
	v_pk_fma_f32 v[82:83], v[144:145], v[84:85], v[82:83]
	v_mov_b32_dpp v91, v71 row_shr:2 row_mask:0xf bank_mask:0xf
	v_pk_fma_f32 v[82:83], v[78:79], v[148:149], v[82:83]
	v_mov_b32_dpp v86, v70 row_shr:1 row_mask:0xf bank_mask:0xf
	v_mul_f32_e32 v84, 0xbfb8aa3b, v82
	v_mul_f32_e32 v85, 0xbfb8aa3b, v83
	v_exp_f32_e32 v84, v84
	v_exp_f32_e32 v85, v85
	v_mov_b32_dpp v87, v71 row_shr:1 row_mask:0xf bank_mask:0xf
	v_pk_fma_f32 v[88:89], v[124:125], v[90:91], v[128:129]
	v_add_f32_e32 v84, 1.0, v84
	v_add_f32_e32 v85, 1.0, v85
	v_rcp_f32_e32 v84, v84
	v_rcp_f32_e32 v85, v85
	v_pk_fma_f32 v[86:87], v[132:133], v[86:87], v[88:89]
	v_cvt_pk_bf16_f32 v80, v80, v81
	v_pk_fma_f32 v[86:87], v[70:71], v[136:137], v[86:87]
	v_pk_mul_f32 v[82:83], v[82:83], v[84:85]
	v_add_u32_e32 v84, 0xa0, v212
	v_pk_mul_f32 v[82:83], v[86:87], v[82:83]
	v_add_u32_e32 v156, v84, v177
	v_cvt_pk_bf16_f32 v81, v82, v83
	v_mad_i64_i32 v[82:83], s[0:1], v156, s74, v[182:183]
	global_store_dwordx2 v[82:83], v[80:81], off
	v_mov_b32_e32 v82, v97
	v_mov_b32_e32 v83, v97
	v_mov_b32_e32 v80, v97
	v_mov_b32_dpp v82, v76 row_ror:2 row_mask:0xf bank_mask:0xf
	v_mov_b32_e32 v81, v97
	v_mov_b32_dpp v83, v77 row_ror:2 row_mask:0xf bank_mask:0xf
	v_mov_b32_dpp v80, v76 row_ror:1 row_mask:0xf bank_mask:0xf
	v_mov_b32_dpp v82, v72 row_shr:2 row_mask:0xf bank_mask:0xf
	v_mov_b32_e32 v76, v97
	v_mov_b32_e32 v84, v97
	v_mov_b32_dpp v81, v77 row_ror:1 row_mask:0xf bank_mask:0xf
	v_mov_b32_dpp v83, v73 row_shr:2 row_mask:0xf bank_mask:0xf
	v_mov_b32_e32 v77, v97
	v_mov_b32_e32 v85, v97
	v_mov_b32_dpp v80, v72 row_shr:1 row_mask:0xf bank_mask:0xf
	v_mov_b32_dpp v76, v68 row_ror:1 row_mask:0xf bank_mask:0xf
	v_mov_b32_dpp v84, v68 row_ror:2 row_mask:0xf bank_mask:0xf
	v_mov_b32_dpp v81, v73 row_shr:1 row_mask:0xf bank_mask:0xf
	v_mov_b32_dpp v77, v69 row_ror:1 row_mask:0xf bank_mask:0xf
	v_mov_b32_dpp v85, v69 row_ror:2 row_mask:0xf bank_mask:0xf
	v_pk_fma_f32 v[68:69], v[138:139], v[82:83], v[150:151]
	v_mov_b32_dpp v84, v64 row_shr:2 row_mask:0xf bank_mask:0xf
	v_pk_fma_f32 v[68:69], v[142:143], v[80:81], v[68:69]
	v_mov_b32_dpp v85, v65 row_shr:2 row_mask:0xf bank_mask:0xf
	v_pk_fma_f32 v[68:69], v[72:73], v[146:147], v[68:69]
	v_mov_b32_dpp v76, v64 row_shr:1 row_mask:0xf bank_mask:0xf
	v_mul_f32_e32 v72, 0xbfb8aa3b, v68
	v_mul_f32_e32 v73, 0xbfb8aa3b, v69
	v_exp_f32_e32 v72, v72
	v_exp_f32_e32 v73, v73
	v_mov_b32_dpp v77, v65 row_shr:1 row_mask:0xf bank_mask:0xf
	v_pk_fma_f32 v[80:81], v[122:123], v[84:85], v[126:127]
	v_add_f32_e32 v72, 1.0, v72
	v_add_f32_e32 v73, 1.0, v73
	v_rcp_f32_e32 v72, v72
	v_rcp_f32_e32 v73, v73
	v_pk_fma_f32 v[76:77], v[130:131], v[76:77], v[80:81]
	v_or_b32_e32 v98, 4, v176
	v_pk_fma_f32 v[64:65], v[64:65], v[134:135], v[76:77]
	v_pk_mul_f32 v[68:69], v[68:69], v[72:73]
	v_mov_b32_e32 v72, v97
	v_mov_b32_e32 v73, v97
	v_pk_mul_f32 v[64:65], v[64:65], v[68:69]
	v_mov_b32_e32 v68, v97
	v_mov_b32_dpp v72, v78 row_ror:2 row_mask:0xf bank_mask:0xf
	v_mov_b32_e32 v69, v97
	v_mov_b32_dpp v73, v79 row_ror:2 row_mask:0xf bank_mask:0xf
	v_mov_b32_dpp v68, v78 row_ror:1 row_mask:0xf bank_mask:0xf
	v_mov_b32_dpp v72, v74 row_shr:2 row_mask:0xf bank_mask:0xf
	v_mov_b32_e32 v76, v97
	v_mov_b32_e32 v78, v97
	v_mov_b32_dpp v69, v79 row_ror:1 row_mask:0xf bank_mask:0xf
	v_mov_b32_dpp v73, v75 row_shr:2 row_mask:0xf bank_mask:0xf
	v_mov_b32_e32 v77, v97
	v_mov_b32_e32 v79, v97
	v_mov_b32_dpp v68, v74 row_shr:1 row_mask:0xf bank_mask:0xf
	v_mov_b32_dpp v76, v70 row_ror:1 row_mask:0xf bank_mask:0xf
	v_mov_b32_dpp v78, v70 row_ror:2 row_mask:0xf bank_mask:0xf
; __device__ __forceinline__ void epi_upc(const EpiP& e, const f32x4 (&acc)[2][2][4][2], const pg8::Unit& u, int wr, int wc, int fr, int fq) {
;     ...
;     const f32x4 wg0 = *(const f32x4*)(cw + ch), wg1 = *(const f32x4*)(cw + NUP + ch), wg2 = *(const f32x4*)(cw + 2 * NUP + ch), bg = *(const f32x4*)(cb + ch);
;     const f32x4 wv0 = *(const f32x4*)(cw + DFF + ch), wv1 = *(const f32x4*)(cw + NUP + DFF + ch), wv2 = *(const f32x4*)(cw + 2 * NUP + DFF + ch), bv = *(const f32x4*)(cb + DFF + ch);
; #pragma unroll
;     for (int ai = 0; ai < 2; ++ai)
; #pragma unroll
;       for (int m = 0; m < 4; ++m) {
;         const int g = ai * 8 + wr * 4 + m, gp = g > 0 ? g - 1 : 0;
;         const f32x4 xg = acc[ai][0][m][n], xv = acc[ai][1][m][n];
;         float y[4];
;         if (m > 0) {
;           const f32x4 pg = acc[ai][0][m - 1][n], pv = acc[ai][1][m - 1][n];
; #pragma unroll
;           for (int k = 0; k < 4; ++k) {
;             const float g1 = dpp_prev1(pg[k], xg[k]), g2 = dpp_prev2(pg[k], xg[k]), v1 = dpp_prev1(pv[k], xv[k]), v2 = dpp_prev2(pv[k], xv[k]);
;             const float cg = bg[k] + wg0[k] * g2 + wg1[k] * g1 + wg2[k] * xg[k];
;             const float cv = bv[k] + wv0[k] * v2 + wv1[k] * v1 + wv2[k] * xv[k];
;             y[k] = silu_mul(cg, cv);
;           }
;         } else {
;           const LAS unsigned char* hp = ex + (gp * 2 * 256 + lc0 + 4 * n) * 2;
;           const u32x2 hg14 = *(const LAS u32x2*)hp, hg15 = *(const LAS u32x2*)(hp + 512), hv14 = *(const LAS u32x2*)(hp + 256), hv15 = *(const LAS u32x2*)(hp + 512 + 256);
;           const float h14g[4] = {bf_lo(hg14.x), bf_hi(hg14.x), bf_lo(hg14.y), bf_hi(hg14.y)}, h15g[4] = {bf_lo(hg15.x), bf_hi(hg15.x), bf_lo(hg15.y), bf_hi(hg15.y)};
;           const float h14v[4] = {bf_lo(hv14.x), bf_hi(hv14.x), bf_lo(hv14.y), bf_hi(hv14.y)}, h15v[4] = {bf_lo(hv15.x), bf_hi(hv15.x), bf_lo(hv15.y), bf_hi(hv15.y)};
; #pragma unroll
;           for (int k = 0; k < 4; ++k) {
;             float g1 = dpp_shr1(xg[k]), g2 = dpp_shr2(xg[k]), v1 = dpp_shr1(xv[k]), v2 = dpp_shr2(xv[k]);
;             if (fr == 0) { g1 = h15g[k]; g2 = h14g[k]; v1 = h15v[k]; v2 = h14v[k]; }
;             if (fr == 1) { g2 = h15g[k]; v2 = h15v[k]; }
;             const float cg = bg[k] + wg0[k] * g2 + wg1[k] * g1 + wg2[k] * xg[k];
;             const float cv = bv[k] + wv0[k] * v2 + wv1[k] * v1 + wv2[k] * xv[k];
	v_mov_b32_dpp v69, v75 row_shr:1 row_mask:0xf bank_mask:0xf
	v_mov_b32_dpp v77, v71 row_ror:1 row_mask:0xf bank_mask:0xf
	v_mov_b32_dpp v79, v71 row_ror:2 row_mask:0xf bank_mask:0xf
	v_pk_fma_f32 v[70:71], v[140:141], v[72:73], v[152:153]
	v_mov_b32_dpp v78, v66 row_shr:2 row_mask:0xf bank_mask:0xf
	v_pk_fma_f32 v[68:69], v[144:145], v[68:69], v[70:71]
	v_mov_b32_dpp v79, v67 row_shr:2 row_mask:0xf bank_mask:0xf
	v_pk_fma_f32 v[68:69], v[74:75], v[148:149], v[68:69]
	v_mov_b32_dpp v76, v66 row_shr:1 row_mask:0xf bank_mask:0xf
	v_mul_f32_e32 v70, 0xbfb8aa3b, v68
	v_mul_f32_e32 v71, 0xbfb8aa3b, v69
	v_exp_f32_e32 v70, v70
	v_exp_f32_e32 v71, v71
	v_mov_b32_dpp v77, v67 row_shr:1 row_mask:0xf bank_mask:0xf
	v_pk_fma_f32 v[72:73], v[124:125], v[78:79], v[128:129]
	v_add_f32_e32 v70, 1.0, v70
	v_add_f32_e32 v71, 1.0, v71
	v_rcp_f32_e32 v70, v70
	v_rcp_f32_e32 v71, v71
	v_pk_fma_f32 v[72:73], v[132:133], v[76:77], v[72:73]
	v_cvt_pk_bf16_f32 v64, v64, v65
	v_pk_fma_f32 v[66:67], v[66:67], v[136:137], v[72:73]
	v_pk_mul_f32 v[68:69], v[68:69], v[70:71]
	v_ashrrev_i32_e32 v99, 31, v98
	v_pk_mul_f32 v[66:67], v[66:67], v[68:69]
	v_add_u32_e32 v68, 0xb0, v212
	v_add_u32_e32 v134, v68, v177
	v_cvt_pk_bf16_f32 v65, v66, v67
	v_mad_i64_i32 v[66:67], s[0:1], v134, s74, v[182:183]
	global_store_dwordx2 v[66:67], v[64:65], off
	v_mov_b32_dpp v141, v60 row_shr:1 row_mask:0xf bank_mask:0xf bound_ctrl:1
	v_mov_b32_dpp v142, v60 row_shr:2 row_mask:0xf bank_mask:0xf bound_ctrl:1
	v_mov_b32_dpp v144, v56 row_shr:1 row_mask:0xf bank_mask:0xf bound_ctrl:1
	v_mov_b32_dpp v143, v56 row_shr:2 row_mask:0xf bank_mask:0xf bound_ctrl:1
	v_mov_b32_dpp v138, v61 row_shr:1 row_mask:0xf bank_mask:0xf bound_ctrl:1
	v_mov_b32_dpp v137, v61 row_shr:2 row_mask:0xf bank_mask:0xf bound_ctrl:1
	v_mov_b32_dpp v140, v57 row_shr:1 row_mask:0xf bank_mask:0xf bound_ctrl:1
	v_mov_b32_dpp v139, v57 row_shr:2 row_mask:0xf bank_mask:0xf bound_ctrl:1
	v_mov_b32_dpp v133, v62 row_shr:1 row_mask:0xf bank_mask:0xf bound_ctrl:1
	v_mov_b32_dpp v132, v62 row_shr:2 row_mask:0xf bank_mask:0xf bound_ctrl:1
	v_mov_b32_dpp v136, v58 row_shr:1 row_mask:0xf bank_mask:0xf bound_ctrl:1
	v_mov_b32_dpp v135, v58 row_shr:2 row_mask:0xf bank_mask:0xf bound_ctrl:1
	v_mov_b32_dpp v129, v63 row_shr:1 row_mask:0xf bank_mask:0xf bound_ctrl:1
	v_mov_b32_dpp v128, v63 row_shr:2 row_mask:0xf bank_mask:0xf bound_ctrl:1
	v_mov_b32_dpp v131, v59 row_shr:1 row_mask:0xf bank_mask:0xf bound_ctrl:1
	v_mov_b32_dpp v130, v59 row_shr:2 row_mask:0xf bank_mask:0xf bound_ctrl:1
	s_waitcnt vmcnt(3)
	v_mov_b64_e32 v[64:65], v[104:105]
	v_mov_b64_e32 v[66:67], v[106:107]
	v_mov_b64_e32 v[72:73], v[108:109]
	v_mov_b64_e32 v[74:75], v[110:111]
	v_mov_b64_e32 v[76:77], v[112:113]
	v_mov_b64_e32 v[78:79], v[114:115]
	v_mov_b64_e32 v[80:81], v[116:117]
	v_mov_b64_e32 v[82:83], v[118:119]
	v_mov_b64_e32 v[68:69], v[190:191]
	v_mov_b64_e32 v[70:71], v[192:193]
	v_mov_b64_e32 v[84:85], v[194:195]
	v_mov_b64_e32 v[86:87], v[196:197]
	v_mov_b64_e32 v[88:89], v[198:199]
	v_mov_b64_e32 v[90:91], v[200:201]
	v_mov_b64_e32 v[92:93], v[202:203]
	v_mov_b64_e32 v[94:95], v[204:205]
	v_mov_b32_e32 v120, v64
	v_mov_b32_e32 v124, v72
	v_mov_b32_e32 v122, v80
	v_mov_b32_e32 v126, v76
	v_mov_b32_e32 v113, v65
	v_mov_b32_e32 v115, v81
	v_mov_b32_e32 v117, v73
	v_mov_b32_e32 v121, v68
	v_mov_b32_e32 v112, v69
	v_mov_b32_e32 v123, v84
	v_mov_b32_e32 v114, v85
	v_mov_b32_e32 v125, v88
	v_mov_b32_e32 v116, v89
	v_mov_b32_e32 v127, v92
	v_mov_b32_e32 v118, v93
	v_mov_b32_e32 v119, v77
	v_mov_b32_e32 v102, v70
	v_mov_b32_e32 v103, v66
	v_mov_b32_e32 v104, v86
	v_mov_b32_e32 v105, v82
	v_mov_b32_e32 v106, v90
	v_mov_b32_e32 v107, v74
	v_mov_b32_e32 v110, v94
	v_mov_b32_e32 v111, v78
	v_mov_b32_e32 v100, v79
	v_mov_b32_e32 v101, v95
	v_mov_b32_e32 v108, v75
	v_mov_b32_e32 v109, v91
	s_and_saveexec_b64 s[0:1], s[38:39]
	s_xor_b64 s[56:57], exec, s[0:1]
	s_cbranch_execz .LBB0_1297
; #define LAS __attribute__((address_space(3)))
; __device__ __forceinline__ float bf_lo(unsigned u) { return __uint_as_float(u << 16); }
; __device__ __forceinline__ float bf_hi(unsigned u) { return __uint_as_float(u & 0xffff0000u); }
; __device__ __forceinline__ float dpp_shr1(float x) { return __int_as_float(__builtin_amdgcn_update_dpp(0, __float_as_int(x), 0x111, 0xF, 0xF, true)); }
; __device__ __forceinline__ float dpp_shr2(float x) { return __int_as_float(__builtin_amdgcn_update_dpp(0, __float_as_int(x), 0x112, 0xF, 0xF, true)); }
; __device__ __forceinline__ float silu_mul(float g, float v) { return g * frcp(1.0f + fexp2(-g * LOG2E)) * v; }
; __device__ __forceinline__ void epi_upc(const EpiP& e, const f32x4 (&acc)[2][2][4][2], const pg8::Unit& u, int wr, int wc, int fr, int fq) {
;     ...
;         } else {
;           const LAS unsigned char* hp = ex + (gp * 2 * 256 + lc0 + 4 * n) * 2;
;           const u32x2 hg14 = *(const LAS u32x2*)hp, hg15 = *(const LAS u32x2*)(hp + 512), hv14 = *(const LAS u32x2*)(hp + 256), hv15 = *(const LAS u32x2*)(hp + 512 + 256);
;           const float h14g[4] = {bf_lo(hg14.x), bf_hi(hg14.x), bf_lo(hg14.y), bf_hi(hg14.y)}, h15g[4] = {bf_lo(hg15.x), bf_hi(hg15.x), bf_lo(hg15.y), bf_hi(hg15.y)};
;           const float h14v[4] = {bf_lo(hv14.x), bf_hi(hv14.x), bf_lo(hv14.y), bf_hi(hv14.y)}, h15v[4] = {bf_lo(hv15.x), bf_hi(hv15.x), bf_lo(hv15.y), bf_hi(hv15.y)};
; #pragma unroll
;           for (int k = 0; k < 4; ++k) {
;             float g1 = dpp_shr1(xg[k]), g2 = dpp_shr2(xg[k]), v1 = dpp_shr1(xv[k]), v2 = dpp_shr2(xv[k]);
;             if (fr == 0) { g1 = h15g[k]; g2 = h14g[k]; v1 = h15v[k]; v2 = h14v[k]; }
;             if (fr == 1) { g2 = h15g[k]; v2 = h15v[k]; }
;             const float cg = bg[k] + wg0[k] * g2 + wg1[k] * g1 + wg2[k] * xg[k];
;             const float cv = bv[k] + wv0[k] * v2 + wv1[k] * v1 + wv2[k] * xv[k];
;             y[k] = silu_mul(cg, cv);
;           }
;         }
;         const int row = u.pm * 256 + ai * 128 + wr * 64 + m * 16 + fr;
;         if (!(g == 0 && fr < 2)) { u32x2 w; w.x = pk2(y[0], y[1]); w.y = pk2(y[2], y[3]); *(u32x2*)(act + (size_t)row * DFF + ch) = w; }
	v_add_u32_e32 v100, s35, v216
	ds_read2_b64 v[146:149], v100 offset1:32
	ds_read2_b64 v[150:153], v100 offset0:64 offset1:96
	s_waitcnt lgkmcnt(0)
	v_and_b32_e32 v145, 0xffff0000, v146
	v_and_b32_e32 v160, 0xffff0000, v148
	v_lshlrev_b32_e32 v108, 16, v150
	v_lshlrev_b32_e32 v148, 16, v148
	v_lshlrev_b32_e32 v146, 16, v146
	v_lshlrev_b32_e32 v109, 16, v152
	v_cndmask_b32_e64 v100, v141, v108, s[4:5]
	v_cndmask_b32_e64 v141, v142, v146, s[4:5]
	v_cndmask_b32_e64 v142, v143, v148, s[4:5]
	v_cndmask_b32_e64 v101, v144, v109, s[4:5]
	v_cndmask_b32_e64 v109, v142, v109, s[6:7]
	v_cndmask_b32_e64 v108, v141, v108, s[6:7]
	v_pk_fma_f32 v[108:109], v[120:121], v[108:109], v[122:123]
	v_and_b32_e32 v150, 0xffff0000, v150
	v_pk_fma_f32 v[100:101], v[124:125], v[100:101], v[108:109]
	v_mov_b32_e32 v108, v60
	v_mov_b32_e32 v109, v56
	v_pk_fma_f32 v[100:101], v[108:109], v[126:127], v[100:101]
	v_and_b32_e32 v152, 0xffff0000, v152
	v_mul_f32_e32 v108, 0xbfb8aa3b, v100
	v_exp_f32_e32 v108, v108
	v_cndmask_b32_e64 v109, v137, v145, s[4:5]
	v_cndmask_b32_e64 v109, v109, v150, s[6:7]
	v_lshlrev_b32_e32 v161, 16, v147
	v_add_f32_e32 v108, 1.0, v108
	v_rcp_f32_e32 v108, v108
	v_lshlrev_b32_e32 v176, 16, v149
	v_lshlrev_b32_e32 v178, 16, v153
	v_lshlrev_b32_e32 v179, 16, v151
	v_mul_f32_e32 v100, v100, v108
	v_cndmask_b32_e64 v108, v139, v160, s[4:5]
	v_cndmask_b32_e64 v108, v108, v152, s[6:7]
	v_mul_f32_e32 v141, v101, v100
	v_cndmask_b32_e64 v101, v138, v150, s[4:5]
	v_cndmask_b32_e64 v100, v140, v152, s[4:5]
	v_pk_fma_f32 v[108:109], v[112:113], v[108:109], v[114:115]
	v_and_b32_e32 v147, 0xffff0000, v147
	v_pk_fma_f32 v[100:101], v[116:117], v[100:101], v[108:109]
	v_mov_b32_e32 v108, v57
	v_mov_b32_e32 v109, v61
	v_pk_fma_f32 v[100:101], v[108:109], v[118:119], v[100:101]
	v_cndmask_b32_e64 v109, v132, v161, s[4:5]
	v_mul_f32_e32 v108, 0xbfb8aa3b, v101
	v_exp_f32_e32 v108, v108
	v_cndmask_b32_e64 v109, v109, v179, s[6:7]
	v_and_b32_e32 v149, 0xffff0000, v149
	v_and_b32_e32 v151, 0xffff0000, v151
	v_add_f32_e32 v108, 1.0, v108
	v_rcp_f32_e32 v108, v108
	v_and_b32_e32 v153, 0xffff0000, v153
	v_cndmask_b32_e64 v132, v130, v149, s[4:5]
	v_cndmask_b32_e64 v132, v132, v153, s[6:7]
	v_mul_f32_e32 v101, v101, v108
	v_cndmask_b32_e64 v108, v135, v176, s[4:5]
	v_cndmask_b32_e64 v108, v108, v178, s[6:7]
	v_mul_f32_e32 v140, v100, v101
	v_cndmask_b32_e64 v101, v133, v179, s[4:5]
	v_cndmask_b32_e64 v100, v136, v178, s[4:5]
	v_pk_fma_f32 v[108:109], v[102:103], v[108:109], v[104:105]
	v_cndmask_b32_e64 v133, v128, v147, s[4:5]
	v_pk_fma_f32 v[100:101], v[106:107], v[100:101], v[108:109]
	v_mov_b32_e32 v108, v58
	v_mov_b32_e32 v109, v62
	v_pk_fma_f32 v[100:101], v[108:109], v[110:111], v[100:101]
	v_cndmask_b32_e64 v133, v133, v151, s[6:7]
	v_mul_f32_e32 v108, 0xbfb8aa3b, v101
	v_exp_f32_e32 v108, v108
	v_mov_b32_e32 v136, v71
	v_mov_b32_e32 v137, v67
	v_mov_b32_e32 v138, v87
	v_add_f32_e32 v108, 1.0, v108
	v_rcp_f32_e32 v108, v108
	v_mov_b32_e32 v139, v83
	v_mov_b32_e32 v130, v91
	v_pk_fma_f32 v[132:133], v[136:137], v[132:133], v[138:139]
	v_mul_f32_e32 v101, v101, v108
	v_mul_f32_e32 v135, v100, v101
	v_cndmask_b32_e64 v101, v129, v151, s[4:5]
	v_cndmask_b32_e64 v100, v131, v153, s[4:5]
	v_mov_b32_e32 v131, v75
	v_mov_b32_e32 v108, v59
	v_mov_b32_e32 v109, v63
	v_mov_b32_e32 v128, v95
	v_mov_b32_e32 v129, v79
	v_pk_fma_f32 v[100:101], v[130:131], v[100:101], v[132:133]
	s_nop 0
	v_pk_fma_f32 v[100:101], v[108:109], v[128:129], v[100:101]
	v_add_u32_e32 v128, v177, v212
	v_mul_f32_e32 v108, 0xbfb8aa3b, v101
	v_exp_f32_e32 v108, v108
	s_nop 0
	v_add_f32_e32 v108, 1.0, v108
	v_rcp_f32_e32 v108, v108
	s_nop 0
	v_mul_f32_e32 v101, v101, v108
	v_mov_b64_e32 v[108:109], s[12:13]
	v_mul_f32_e32 v101, v100, v101
	v_mad_i64_i32 v[108:109], s[0:1], v128, s74, v[108:109]
	v_cvt_pk_bf16_f32 v100, v141, v140
	v_cvt_pk_bf16_f32 v101, v135, v101
	v_lshl_add_u64 v[108:109], v[98:99], 1, v[108:109]
	global_store_dwordx2 v[108:109], v[100:101], off
	v_mov_b32_e32 v100, v79
	v_mov_b32_e32 v101, v95
	v_mov_b32_e32 v108, v75
	v_mov_b32_e32 v109, v91
